# v043 + packed f32 ops in the EpiC conv+silu epilogue (P9) split into scalar pairs
# baseline (speedup 1.0000x reference)
; #define LAS __attribute__((address_space(3)))
;     __device__ __forceinline__ void operator()(const f32x4 (&acc)[2][2][4][2], const CU2& u, int wr, int wc, int fr_, int fq_) const {
;     ...
;         if (wr == 0 && fr == 15) {
; #pragma unroll
;             for (int bj = 0; bj < 2; ++bj)
; #pragma unroll
;                 for (int n = 0; n < 2; ++n) { *(LAS f32x4*)(hal + 128 * bj + cl + 4 * n) = acc[1][bj][2][n] * rsv[6]; *(LAS f32x4*)(hal + 256 + 128 * bj + cl + 4 * n) = acc[1][bj][3][n] * rsv[7]; }
;         }
;         asm volatile("s_waitcnt lgkmcnt(0)" ::: "memory"); __builtin_amdgcn_s_barrier(); asm volatile("" ::: "memory");
;     ...
;             f32x4 pg2 = acc[1][0][2][n] * rsv[6], pg1 = acc[1][0][3][n] * rsv[7], pv2 = acc[1][1][2][n] * rsv[6], pv1 = acc[1][1][3][n] * rsv[7];
.LBB0_925:
	s_or_b64 exec, exec, s[0:1]
	v_cmp_ne_u32_e32 vcc, 15, v184
	s_xor_b64 s[0:1], s[16:17], -1
	v_mov_b32_e32 v233, v232
	v_mov_b32_e32 v231, v230
	s_or_b64 s[0:1], s[0:1], vcc
	s_waitcnt vmcnt(0) lgkmcnt(0)
	v_mul_f32_e32 v128, v80, v230
	v_mul_f32_e32 v129, v81, v231
	v_mul_f32_e32 v132, v84, v232
	v_mul_f32_e32 v133, v85, v233
	v_mul_f32_e32 v136, v76, v230
	v_mul_f32_e32 v137, v77, v231
	s_and_saveexec_b64 s[4:5], s[0:1]
	s_xor_b64 s[0:1], exec, s[4:5]
	v_mov_b32_e32 v52, v230
	v_mov_b32_e32 v53, v230
	v_mov_b32_e32 v62, v232
	v_mov_b32_e32 v63, v232
	v_mul_f32_e32 v130, v82, v52
	v_mul_f32_e32 v131, v83, v53
	v_mul_f32_e32 v134, v86, v62
	v_mul_f32_e32 v135, v87, v63
	v_mul_f32_e32 v138, v78, v52
	v_mul_f32_e32 v139, v79, v53
	s_or_saveexec_b64 s[0:1], s[0:1]
	v_mul_f32_e32 v142, v50, v232
	v_mul_f32_e32 v143, v51, v232
	v_mul_f32_e32 v140, v48, v232
	v_mul_f32_e32 v141, v49, v232
	v_lshl_add_u32 v76, v226, 2, 0
	v_mul_f32_e32 v48, v72, v232
	v_mul_f32_e32 v49, v73, v233
	v_mul_f32_e32 v52, v68, v230
	v_mul_f32_e32 v53, v69, v231
	v_mul_f32_e32 v62, v54, v232
	v_mul_f32_e32 v63, v55, v233
	v_mul_f32_e32 v66, v44, v230
	v_mul_f32_e32 v67, v45, v231
	s_xor_b64 exec, exec, s[0:1]
	s_cbranch_execz .LBB0_929
	v_mov_b32_e32 v231, v230
	v_mul_f32_e32 v130, v82, v230
	v_mul_f32_e32 v131, v83, v231
	v_add_u32_e32 v45, 0x20400, v76
	v_mov_b32_e32 v233, v232
	ds_write_b128 v45, v[128:131]
	v_mul_f32_e32 v134, v86, v232
	v_mul_f32_e32 v135, v87, v233
	v_add_u32_e32 v45, 0x20200, v76
	v_add_u32_e32 v44, 0x20000, v76
	v_mul_f32_e32 v50, v74, v232
	v_mul_f32_e32 v51, v75, v233
	v_mul_f32_e32 v54, v70, v230
	v_mul_f32_e32 v55, v71, v231
	ds_write_b128 v45, v[132:135]
	v_mul_f32_e32 v138, v78, v230
	v_mul_f32_e32 v139, v79, v231
	v_add_u32_e32 v45, 0x20600, v76
	v_mul_f32_e32 v64, v56, v232
	v_mul_f32_e32 v65, v57, v233
	v_mul_f32_e32 v68, v46, v230
	v_mul_f32_e32 v69, v47, v231
	ds_write_b128 v44, v[140:143]
	ds_write_b128 v44, v[48:51] offset:16
	ds_write_b128 v44, v[52:55] offset:1040
	ds_write_b128 v45, v[136:139]
	ds_write_b128 v44, v[62:65] offset:528
	ds_write_b128 v44, v[66:69] offset:1552

; __device__ __forceinline__ unsigned cvt_pk_bf16(float lo, float hi) { unsigned r; asm("v_cvt_pk_bf16_f32 %0, %1, %2" : "=v"(r) : "v"(lo), "v"(hi)); return r; }
;     __device__ __forceinline__ void operator()(const f32x4 (&acc)[2][2][4][2], const CU2& u, int wr, int wc, int fr_, int fq_) const {
;     ...
;             for (int j = 0; j < 8; ++j) {
;                 const f32x4 xg = acc[j >> 2][0][j & 3][n] * rsv[j], xv = acc[j >> 2][1][j & 3][n] * rsv[j];
;                 const f32x4 gc = gb + g2 * xg + g1 * pg1 + g0 * pg2, vc = vb + v2 * xv + v1 * pv1 + v0 * pv2;
;                 f32x4 sg;
; #pragma unroll
;                 for (int e = 0; e < 4; ++e) sg[e] = __builtin_amdgcn_rcpf(1.f + __expf(-gc[e]));
;                 const f32x4 o4 = gc * sg * vc;
;                 pg2 = pg1; pg1 = xg; pv2 = pv1; pv1 = xv;
;                 if (rb + j >= 2 && tb + j < T_) { u32x2 w; w.x = cvt_pk_bf16(o4[0], o4[1]); w.y = cvt_pk_bf16(o4[2], o4[3]); *(u32x2*)(act + (size_t)(tb + j) * FF_ + 128 * u.pn + cl + 4 * n) = w; }
.LBB0_931:
	s_or_b64 exec, exec, s[6:7]
	s_lshl_b64 s[0:1], s[0:1], 1
	s_add_u32 s0, s44, s0
	s_addc_u32 s1, s45, s1
	v_lshl_add_u64 v[50:51], v[226:227], 1, s[0:1]
	v_cmp_lt_i32_e32 vcc, 1, v225
	v_cmp_gt_i32_e64 s[0:1], s89, v200
	v_mul_f32_e32 v80, v150, v228
	v_mul_f32_e32 v81, v151, v228
	v_mul_f32_e32 v68, v148, v228
	v_mul_f32_e32 v69, v149, v228
	v_mul_f32_e32 v130, v146, v228
	v_mul_f32_e32 v131, v147, v228
	v_mul_f32_e32 v134, v144, v228
	v_mul_f32_e32 v135, v145, v228
	s_and_b64 s[10:11], vcc, s[0:1]
	s_and_saveexec_b64 s[0:1], s[10:11]
	s_cbranch_execz .LBB0_933
	s_waitcnt lgkmcnt(0)
	v_fma_f32 v84, v80, v166, v170
	v_fma_f32 v85, v81, v167, v171
	v_fma_f32 v138, v68, v164, v168
	v_fma_f32 v139, v69, v165, v169
	s_waitcnt lgkmcnt(2)
	v_fma_f32 v84, v162, v186, v84
	v_fma_f32 v85, v163, v187, v85
	v_fma_f32 v138, v160, v184, v138
	v_fma_f32 v139, v161, v185, v139
	v_fma_f32 v84, v154, v194, v84
	v_fma_f32 v85, v155, v195, v85
	v_fma_f32 v138, v152, v192, v138
	v_fma_f32 v139, v153, v193, v139
	v_mul_f32_e32 v146, 0xbfb8aa3b, v84
	v_mul_f32_e32 v144, 0xbfb8aa3b, v138
	v_mul_f32_e32 v145, 0xbfb8aa3b, v139
	v_mul_f32_e32 v147, 0xbfb8aa3b, v85
	v_exp_f32_e32 v144, v144
	v_exp_f32_e32 v145, v145
	v_exp_f32_e32 v146, v146
	v_exp_f32_e32 v147, v147
	v_add_f32_e32 v144, 1.0, v144
	v_add_f32_e32 v145, 1.0, v145
	v_add_f32_e32 v146, 1.0, v146
	v_add_f32_e32 v147, 1.0, v147
	v_rcp_f32_e32 v144, v144
	v_rcp_f32_e32 v145, v145
	v_rcp_f32_e32 v146, v146
	v_rcp_f32_e32 v147, v147
	s_waitcnt lgkmcnt(0)
	v_fma_f32 v72, v130, v178, v182
	v_fma_f32 v73, v131, v179, v183
	v_fma_f32 v76, v134, v176, v180
	v_fma_f32 v77, v135, v177, v181
	s_waitcnt lgkmcnt(0)
	v_fma_f32 v72, v174, v190, v72
	v_fma_f32 v73, v175, v191, v73
	v_fma_f32 v76, v172, v188, v76
	v_fma_f32 v77, v173, v189, v77
	v_fma_f32 v72, v158, v198, v72
	v_fma_f32 v73, v159, v199, v73
	v_fma_f32 v76, v156, v196, v76
	v_fma_f32 v77, v157, v197, v77
	v_mul_f32_e32 v84, v84, v146
	v_mul_f32_e32 v85, v85, v147
	v_mul_f32_e32 v138, v138, v144
	v_mul_f32_e32 v139, v139, v145
	v_mul_f32_e32 v72, v72, v84
	v_mul_f32_e32 v73, v73, v85
	v_mul_f32_e32 v76, v76, v138
	v_mul_f32_e32 v77, v77, v139
	s_nop 0
	v_cvt_pk_bf16_f32 v148, v76, v77
	v_cvt_pk_bf16_f32 v149, v72, v73
.LBB0_933:
	s_or_b64 exec, exec, s[0:1]
	s_movk_i32 s0, 0x1fff
	v_cmp_lt_i32_e32 vcc, 0, v225
	v_cmp_gt_i32_e64 s[0:1], s0, v200
	v_mul_f32_e32 v126, v126, v224
	v_mul_f32_e32 v127, v127, v224
	v_mul_f32_e32 v76, v124, v224
	v_mul_f32_e32 v77, v125, v224
	v_mul_f32_e32 v122, v122, v224
	v_mul_f32_e32 v123, v123, v224
	v_mul_f32_e32 v120, v120, v224
	v_mul_f32_e32 v121, v121, v224
	s_and_b64 s[6:7], vcc, s[0:1]
	s_and_saveexec_b64 s[0:1], s[6:7]
	s_cbranch_execz .LBB0_935
	v_fma_f32 v124, v126, v166, v170
	v_fma_f32 v125, v127, v167, v171
	v_fma_f32 v138, v76, v164, v168
	v_fma_f32 v139, v77, v165, v169
	v_fma_f32 v124, v80, v162, v124
	v_fma_f32 v125, v81, v163, v125
	v_fma_f32 v138, v68, v160, v138
	v_fma_f32 v139, v69, v161, v139
	s_waitcnt lgkmcnt(0)
	v_fma_f32 v124, v154, v186, v124
	v_fma_f32 v125, v155, v187, v125
	v_fma_f32 v138, v152, v184, v138
	v_fma_f32 v139, v153, v185, v139
	v_mul_f32_e32 v146, 0xbfb8aa3b, v124
	v_mul_f32_e32 v144, 0xbfb8aa3b, v138
	v_mul_f32_e32 v145, 0xbfb8aa3b, v139
	v_mul_f32_e32 v147, 0xbfb8aa3b, v125
	v_exp_f32_e32 v144, v144
	v_exp_f32_e32 v145, v145
	v_exp_f32_e32 v146, v146
	v_exp_f32_e32 v147, v147
	v_add_f32_e32 v144, 1.0, v144
	v_add_f32_e32 v145, 1.0, v145
	v_add_f32_e32 v146, 1.0, v146
	v_add_f32_e32 v147, 1.0, v147
	v_rcp_f32_e32 v144, v144
	v_rcp_f32_e32 v145, v145
	v_rcp_f32_e32 v146, v146
	v_rcp_f32_e32 v147, v147
	v_fma_f32 v72, v122, v178, v182
	v_fma_f32 v73, v123, v179, v183
	v_fma_f32 v84, v120, v176, v180
	v_fma_f32 v85, v121, v177, v181
	v_fma_f32 v72, v130, v174, v72
	v_fma_f32 v73, v131, v175, v73
	v_fma_f32 v84, v134, v172, v84
	v_fma_f32 v85, v135, v173, v85
	v_fma_f32 v72, v158, v190, v72
	v_fma_f32 v73, v159, v191, v73
	v_fma_f32 v84, v156, v188, v84
	v_fma_f32 v85, v157, v189, v85
	v_mul_f32_e32 v124, v124, v146
	v_mul_f32_e32 v125, v125, v147
	v_mul_f32_e32 v138, v138, v144
	v_mul_f32_e32 v139, v139, v145
	v_mul_f32_e32 v72, v72, v124
	v_mul_f32_e32 v73, v73, v125
	v_mul_f32_e32 v84, v84, v138
	v_mul_f32_e32 v85, v85, v139
	s_nop 0
	v_cvt_pk_bf16_f32 v144, v84, v85
	v_cvt_pk_bf16_f32 v145, v72, v73
.LBB0_935:
	s_or_b64 exec, exec, s[0:1]
	v_cmp_lt_i32_e32 vcc, -1, v225
	v_cmp_gt_i32_e64 s[0:1], s89, v221
	v_mul_f32_e32 v84, v118, v222
	v_mul_f32_e32 v85, v119, v222
	v_mul_f32_e32 v72, v116, v222
	v_mul_f32_e32 v73, v117, v222
	v_mul_f32_e32 v114, v114, v222
	v_mul_f32_e32 v115, v115, v222
	v_mul_f32_e32 v112, v112, v222
	v_mul_f32_e32 v113, v113, v222
	s_and_b64 s[8:9], vcc, s[0:1]
	s_and_saveexec_b64 s[0:1], s[8:9]
	s_cbranch_execz .LBB0_937
	v_fma_f32 v116, v114, v178, v182
	v_fma_f32 v117, v115, v179, v183
	v_fma_f32 v124, v84, v166, v170
	v_fma_f32 v125, v85, v167, v171
	v_fma_f32 v116, v122, v174, v116
	v_fma_f32 v117, v123, v175, v117
	v_fma_f32 v124, v126, v162, v124
	v_fma_f32 v125, v127, v163, v125
	v_fma_f32 v116, v130, v158, v116
	v_fma_f32 v117, v131, v159, v117
	v_fma_f32 v130, v72, v164, v168
	v_fma_f32 v131, v73, v165, v169
	v_fma_f32 v80, v80, v154, v124
	v_fma_f32 v81, v81, v155, v125
	v_fma_f32 v130, v76, v160, v130
	v_fma_f32 v131, v77, v161, v131
	v_fma_f32 v118, v112, v176, v180
	v_fma_f32 v119, v113, v177, v181
	v_fma_f32 v68, v68, v152, v130
	v_fma_f32 v69, v69, v153, v131
	v_mul_f32_e32 v130, 0xbfb8aa3b, v80
	v_mul_f32_e32 v124, 0xbfb8aa3b, v68
	v_mul_f32_e32 v125, 0xbfb8aa3b, v69
	v_mul_f32_e32 v131, 0xbfb8aa3b, v81
	v_exp_f32_e32 v124, v124
	v_exp_f32_e32 v125, v125
	v_exp_f32_e32 v130, v130
	v_exp_f32_e32 v131, v131
	v_add_f32_e32 v124, 1.0, v124
	v_add_f32_e32 v125, 1.0, v125
	v_add_f32_e32 v130, 1.0, v130
	v_add_f32_e32 v131, 1.0, v131
	v_rcp_f32_e32 v124, v124
	v_rcp_f32_e32 v125, v125
	v_rcp_f32_e32 v130, v130
	v_rcp_f32_e32 v131, v131
	v_fma_f32 v118, v120, v172, v118
	v_fma_f32 v119, v121, v173, v119
	v_mul_f32_e32 v68, v68, v124
	v_mul_f32_e32 v69, v69, v125
	v_fma_f32 v118, v134, v156, v118
	v_fma_f32 v119, v135, v157, v119
	v_mul_f32_e32 v80, v80, v130
	v_mul_f32_e32 v81, v81, v131
	v_mul_f32_e32 v68, v118, v68
	v_mul_f32_e32 v69, v119, v69
	v_mul_f32_e32 v80, v116, v80
	v_mul_f32_e32 v81, v117, v81
	v_cvt_pk_bf16_f32 v184, v68, v69
	s_nop 0
	v_cvt_pk_bf16_f32 v185, v80, v81
; __device__ __forceinline__ unsigned cvt_pk_bf16(float lo, float hi) { unsigned r; asm("v_cvt_pk_bf16_f32 %0, %1, %2" : "=v"(r) : "v"(lo), "v"(hi)); return r; }
;     __device__ __forceinline__ void operator()(const f32x4 (&acc)[2][2][4][2], const CU2& u, int wr, int wc, int fr_, int fq_) const {
;     ...
;             for (int j = 0; j < 8; ++j) {
;                 const f32x4 xg = acc[j >> 2][0][j & 3][n] * rsv[j], xv = acc[j >> 2][1][j & 3][n] * rsv[j];
;                 const f32x4 gc = gb + g2 * xg + g1 * pg1 + g0 * pg2, vc = vb + v2 * xv + v1 * pv1 + v0 * pv2;
;                 f32x4 sg;
; #pragma unroll
;                 for (int e = 0; e < 4; ++e) sg[e] = __builtin_amdgcn_rcpf(1.f + __expf(-gc[e]));
;                 const f32x4 o4 = gc * sg * vc;
;                 pg2 = pg1; pg1 = xg; pv2 = pv1; pv1 = xv;
;                 if (rb + j >= 2 && tb + j < T_) { u32x2 w; w.x = cvt_pk_bf16(o4[0], o4[1]); w.y = cvt_pk_bf16(o4[2], o4[3]); *(u32x2*)(act + (size_t)(tb + j) * FF_ + 128 * u.pn + cl + 4 * n) = w; }
.LBB0_937:
	s_or_b64 exec, exec, s[0:1]
	s_movk_i32 s0, 0x1ffd
	v_cmp_lt_i32_e32 vcc, -2, v225
	v_cmp_gt_i32_e64 s[0:1], s0, v200
	v_mul_f32_e32 v80, v110, v220
	v_mul_f32_e32 v81, v111, v220
	v_mul_f32_e32 v68, v108, v220
	v_mul_f32_e32 v69, v109, v220
	v_mul_f32_e32 v106, v106, v220
	v_mul_f32_e32 v107, v107, v220
	v_mul_f32_e32 v104, v104, v220
	v_mul_f32_e32 v105, v105, v220
	s_and_b64 s[12:13], vcc, s[0:1]
	s_and_saveexec_b64 s[0:1], s[12:13]
	s_cbranch_execz .LBB0_939
	v_fma_f32 v116, v80, v166, v170
	v_fma_f32 v117, v81, v167, v171
	v_fma_f32 v118, v68, v164, v168
	v_fma_f32 v119, v69, v165, v169
	v_fma_f32 v110, v104, v176, v180
	v_fma_f32 v111, v105, v177, v181
	v_fma_f32 v116, v84, v162, v116
	v_fma_f32 v117, v85, v163, v117
	v_fma_f32 v118, v72, v160, v118
	v_fma_f32 v119, v73, v161, v119
	v_fma_f32 v110, v112, v172, v110
	v_fma_f32 v111, v113, v173, v111
	v_fma_f32 v116, v126, v154, v116
	v_fma_f32 v117, v127, v155, v117
	v_fma_f32 v76, v76, v152, v118
	v_fma_f32 v77, v77, v153, v119
	v_fma_f32 v110, v120, v156, v110
	v_fma_f32 v111, v121, v157, v111
	v_mul_f32_e32 v118, 0xbfb8aa3b, v76
	v_mul_f32_e32 v119, 0xbfb8aa3b, v77
	v_mul_f32_e32 v120, 0xbfb8aa3b, v116
	v_mul_f32_e32 v121, 0xbfb8aa3b, v117
	v_exp_f32_e32 v118, v118
	v_exp_f32_e32 v119, v119
	v_exp_f32_e32 v120, v120
	v_exp_f32_e32 v121, v121
	v_add_f32_e32 v118, 1.0, v118
	v_add_f32_e32 v119, 1.0, v119
	v_add_f32_e32 v120, 1.0, v120
	v_add_f32_e32 v121, 1.0, v121
	v_rcp_f32_e32 v118, v118
	v_rcp_f32_e32 v119, v119
	v_rcp_f32_e32 v120, v120
	v_rcp_f32_e32 v121, v121
	v_fma_f32 v108, v106, v178, v182
	v_fma_f32 v109, v107, v179, v183
	v_mul_f32_e32 v76, v76, v118
	v_mul_f32_e32 v77, v77, v119
	v_fma_f32 v108, v114, v174, v108
	v_fma_f32 v109, v115, v175, v109
	v_mul_f32_e32 v116, v116, v120
	v_mul_f32_e32 v117, v117, v121
	v_fma_f32 v108, v122, v158, v108
	v_fma_f32 v109, v123, v159, v109
	v_mul_f32_e32 v76, v110, v76
	v_mul_f32_e32 v77, v111, v77
	v_mul_f32_e32 v108, v108, v116
	v_mul_f32_e32 v109, v109, v117
	v_cvt_pk_bf16_f32 v188, v76, v77
	s_nop 0
	v_cvt_pk_bf16_f32 v189, v108, v109
.LBB0_939:
	s_or_b64 exec, exec, s[0:1]
	s_movk_i32 s0, 0x1ffc
	v_cmp_lt_i32_e32 vcc, -3, v225
	v_cmp_gt_i32_e64 s[0:1], s0, v200
	v_mul_f32_e32 v102, v102, v218
	v_mul_f32_e32 v103, v103, v218
	v_mul_f32_e32 v76, v100, v218
	v_mul_f32_e32 v77, v101, v218
	v_mul_f32_e32 v98, v98, v218
	v_mul_f32_e32 v99, v99, v218
	v_mul_f32_e32 v96, v96, v218
	v_mul_f32_e32 v97, v97, v218
	s_and_b64 s[14:15], vcc, s[0:1]
	s_and_saveexec_b64 s[0:1], s[14:15]
	s_cbranch_execz .LBB0_941
	v_fma_f32 v108, v96, v176, v180
	v_fma_f32 v109, v97, v177, v181
	v_fma_f32 v110, v102, v166, v170
	v_fma_f32 v111, v103, v167, v171
	v_fma_f32 v108, v104, v172, v108
	v_fma_f32 v109, v105, v173, v109
	v_fma_f32 v110, v80, v162, v110
	v_fma_f32 v111, v81, v163, v111
	v_fma_f32 v108, v112, v156, v108
	v_fma_f32 v109, v113, v157, v109
	v_fma_f32 v112, v76, v164, v168
	v_fma_f32 v113, v77, v165, v169
	v_fma_f32 v84, v84, v154, v110
	v_fma_f32 v85, v85, v155, v111
	v_fma_f32 v112, v68, v160, v112
	v_fma_f32 v113, v69, v161, v113
	v_fma_f32 v100, v98, v178, v182
	v_fma_f32 v101, v99, v179, v183
	v_fma_f32 v72, v72, v152, v112
	v_fma_f32 v73, v73, v153, v113
	v_mul_f32_e32 v112, 0xbfb8aa3b, v84
	v_mul_f32_e32 v110, 0xbfb8aa3b, v72
	v_mul_f32_e32 v111, 0xbfb8aa3b, v73
	v_mul_f32_e32 v113, 0xbfb8aa3b, v85
	v_exp_f32_e32 v110, v110
	v_exp_f32_e32 v111, v111
	v_exp_f32_e32 v112, v112
	v_exp_f32_e32 v113, v113
	v_add_f32_e32 v110, 1.0, v110
	v_add_f32_e32 v111, 1.0, v111
	v_add_f32_e32 v112, 1.0, v112
	v_add_f32_e32 v113, 1.0, v113
	v_rcp_f32_e32 v110, v110
	v_rcp_f32_e32 v111, v111
	v_rcp_f32_e32 v112, v112
	v_rcp_f32_e32 v113, v113
	v_fma_f32 v100, v106, v174, v100
	v_fma_f32 v101, v107, v175, v101
	v_mul_f32_e32 v72, v72, v110
	v_mul_f32_e32 v73, v73, v111
	v_fma_f32 v100, v114, v158, v100
	v_fma_f32 v101, v115, v159, v101
	v_mul_f32_e32 v84, v84, v112
	v_mul_f32_e32 v85, v85, v113
	v_mul_f32_e32 v72, v108, v72
	v_mul_f32_e32 v73, v109, v73
	v_mul_f32_e32 v84, v100, v84
	v_mul_f32_e32 v85, v101, v85
	v_cvt_pk_bf16_f32 v192, v72, v73
	s_nop 0
	v_cvt_pk_bf16_f32 v193, v84, v85
.LBB0_941:
	s_or_b64 exec, exec, s[0:1]
	s_movk_i32 s0, 0x1ffb
	v_cmp_lt_i32_e32 vcc, -4, v225
	v_cmp_gt_i32_e64 s[0:1], s0, v200
	v_mul_f32_e32 v94, v94, v216
	v_mul_f32_e32 v95, v95, v216
	v_mul_f32_e32 v92, v92, v216
	v_mul_f32_e32 v93, v93, v216
	v_mul_f32_e32 v72, v90, v216
	v_mul_f32_e32 v73, v91, v216
	v_mul_f32_e32 v84, v88, v216
	v_mul_f32_e32 v85, v89, v216
	s_and_b64 s[26:27], vcc, s[0:1]
	s_and_saveexec_b64 s[0:1], s[26:27]
	s_cbranch_execz .LBB0_943
	v_fma_f32 v90, v84, v176, v180
	v_fma_f32 v91, v85, v177, v181
	v_fma_f32 v100, v94, v166, v170
	v_fma_f32 v101, v95, v167, v171
	v_fma_f32 v90, v96, v172, v90
	v_fma_f32 v91, v97, v173, v91
	v_fma_f32 v100, v102, v162, v100
	v_fma_f32 v101, v103, v163, v101
	v_fma_f32 v90, v104, v156, v90
	v_fma_f32 v91, v105, v157, v91
	v_fma_f32 v104, v92, v164, v168
	v_fma_f32 v105, v93, v165, v169
	v_fma_f32 v80, v80, v154, v100
	v_fma_f32 v81, v81, v155, v101
	v_fma_f32 v104, v76, v160, v104
	v_fma_f32 v105, v77, v161, v105
	v_fma_f32 v88, v72, v178, v182
	v_fma_f32 v89, v73, v179, v183
	v_fma_f32 v68, v68, v152, v104
	v_fma_f32 v69, v69, v153, v105
	v_mul_f32_e32 v104, 0xbfb8aa3b, v80
	v_mul_f32_e32 v100, 0xbfb8aa3b, v68
	v_mul_f32_e32 v101, 0xbfb8aa3b, v69
	v_mul_f32_e32 v105, 0xbfb8aa3b, v81
	v_exp_f32_e32 v100, v100
	v_exp_f32_e32 v101, v101
	v_exp_f32_e32 v104, v104
	v_exp_f32_e32 v105, v105
	v_add_f32_e32 v100, 1.0, v100
	v_add_f32_e32 v101, 1.0, v101
	v_add_f32_e32 v104, 1.0, v104
	v_add_f32_e32 v105, 1.0, v105
	v_rcp_f32_e32 v100, v100
	v_rcp_f32_e32 v101, v101
	v_rcp_f32_e32 v104, v104
	v_rcp_f32_e32 v105, v105
	v_fma_f32 v88, v98, v174, v88
	v_fma_f32 v89, v99, v175, v89
	v_mul_f32_e32 v68, v68, v100
	v_mul_f32_e32 v69, v69, v101
	v_fma_f32 v88, v106, v158, v88
	v_fma_f32 v89, v107, v159, v89
	v_mul_f32_e32 v80, v80, v104
	v_mul_f32_e32 v81, v81, v105
	v_mul_f32_e32 v68, v90, v68
	v_mul_f32_e32 v69, v91, v69
	v_mul_f32_e32 v80, v88, v80
	v_mul_f32_e32 v81, v89, v81
	v_cvt_pk_bf16_f32 v196, v68, v69
	s_nop 0
	v_cvt_pk_bf16_f32 v197, v80, v81
; #define LAS __attribute__((address_space(3)))
;     __device__ __forceinline__ void operator()(const f32x4 (&acc)[2][2][4][2], const CU2& u, int wr, int wc, int fr_, int fq_) const {
;     ...
;         for (int n = 0; n < 2; ++n) {
;             const float* wp = cw + 128 * u.pn + cl + 4 * n; const float* bp = cb + 128 * u.pn + cl + 4 * n;
;             const f32x4 g0 = *(const f32x4*)wp, g1 = *(const f32x4*)(wp + 2 * FF_), g2 = *(const f32x4*)(wp + 4 * FF_), gb = *(const f32x4*)bp;
;             const f32x4 v0 = *(const f32x4*)(wp + FF_), v1 = *(const f32x4*)(wp + 3 * FF_), v2 = *(const f32x4*)(wp + 5 * FF_), vb = *(const f32x4*)(bp + FF_);
;             f32x4 pg2 = acc[1][0][2][n] * rsv[6], pg1 = acc[1][0][3][n] * rsv[7], pv2 = acc[1][1][2][n] * rsv[6], pv1 = acc[1][1][3][n] * rsv[7];
; #pragma unroll
;             for (int e = 0; e < 4; ++e) {
;                 pg2[e] = __int_as_float(__builtin_amdgcn_mov_dpp(__float_as_int(pg2[e]), 0x111, 0xF, 0xF, true)); pg1[e] = __int_as_float(__builtin_amdgcn_mov_dpp(__float_as_int(pg1[e]), 0x111, 0xF, 0xF, true));
;                 pv2[e] = __int_as_float(__builtin_amdgcn_mov_dpp(__float_as_int(pv2[e]), 0x111, 0xF, 0xF, true)); pv1[e] = __int_as_float(__builtin_amdgcn_mov_dpp(__float_as_int(pv1[e]), 0x111, 0xF, 0xF, true));
;             }
;             if (fr == 0 && wr == 1) { pg2 = *(const LAS f32x4*)(hal + cl + 4 * n); pg1 = *(const LAS f32x4*)(hal + 256 + cl + 4 * n); pv2 = *(const LAS f32x4*)(hal + 128 + cl + 4 * n); pv1 = *(const LAS f32x4*)(hal + 384 + cl + 4 * n); }
; #pragma unroll
;             for (int j = 0; j < 8; ++j) {
;                 const f32x4 xg = acc[j >> 2][0][j & 3][n] * rsv[j], xv = acc[j >> 2][1][j & 3][n] * rsv[j];
;                 const f32x4 gc = gb + g2 * xg + g1 * pg1 + g0 * pg2, vc = vb + v2 * xv + v1 * pv1 + v0 * pv2;
;                 f32x4 sg;
; #pragma unroll
;                 for (int e = 0; e < 4; ++e) sg[e] = __builtin_amdgcn_rcpf(1.f + __expf(-gc[e]));
;                 const f32x4 o4 = gc * sg * vc;
;                 pg2 = pg1; pg1 = xg; pv2 = pv1; pv1 = xv;
;                 if (rb + j >= 2 && tb + j < T_) { u32x2 w; w.x = cvt_pk_bf16(o4[0], o4[1]); w.y = cvt_pk_bf16(o4[2], o4[3]); *(u32x2*)(act + (size_t)(tb + j) * FF_ + 128 * u.pn + cl + 4 * n) = w; }
.LBB0_943:
	s_or_b64 exec, exec, s[0:1]
	s_movk_i32 s0, 0x1ffa
	v_mov_b32_e32 v233, v232
	v_cmp_lt_i32_e32 vcc, -5, v225
	v_cmp_gt_i32_e64 s[0:1], s0, v200
	v_mul_f32_e32 v68, v86, v232
	v_mul_f32_e32 v69, v87, v233
	s_and_b64 s[28:29], vcc, s[0:1]
	s_and_saveexec_b64 s[0:1], s[28:29]
	s_cbranch_execz .LBB0_945
	v_fma_f32 v88, v142, v166, v170
	v_fma_f32 v89, v143, v167, v171
	v_fma_f32 v90, v140, v164, v168
	v_fma_f32 v91, v141, v165, v169
	v_fma_f32 v86, v132, v176, v180
	v_fma_f32 v87, v133, v177, v181
	v_fma_f32 v88, v94, v162, v88
	v_fma_f32 v89, v95, v163, v89
	v_fma_f32 v90, v92, v160, v90
	v_fma_f32 v91, v93, v161, v91
	v_fma_f32 v86, v84, v172, v86
	v_fma_f32 v87, v85, v173, v87
	v_fma_f32 v88, v102, v154, v88
	v_fma_f32 v89, v103, v155, v89
	v_fma_f32 v76, v76, v152, v90
	v_fma_f32 v77, v77, v153, v91
	v_fma_f32 v86, v96, v156, v86
	v_fma_f32 v87, v97, v157, v87
	v_mul_f32_e32 v90, 0xbfb8aa3b, v76
	v_mul_f32_e32 v91, 0xbfb8aa3b, v77
	v_mul_f32_e32 v96, 0xbfb8aa3b, v88
	v_mul_f32_e32 v97, 0xbfb8aa3b, v89
	v_exp_f32_e32 v90, v90
	v_exp_f32_e32 v91, v91
	v_exp_f32_e32 v96, v96
	v_exp_f32_e32 v97, v97
	v_add_f32_e32 v90, 1.0, v90
	v_add_f32_e32 v91, 1.0, v91
	v_add_f32_e32 v96, 1.0, v96
	v_add_f32_e32 v97, 1.0, v97
	v_rcp_f32_e32 v90, v90
	v_rcp_f32_e32 v91, v91
	v_rcp_f32_e32 v96, v96
	v_rcp_f32_e32 v97, v97
	v_fma_f32 v80, v68, v178, v182
	v_fma_f32 v81, v69, v179, v183
	v_mul_f32_e32 v76, v76, v90
	v_mul_f32_e32 v77, v77, v91
	v_fma_f32 v80, v72, v174, v80
	v_fma_f32 v81, v73, v175, v81
	v_mul_f32_e32 v88, v88, v96
	v_mul_f32_e32 v89, v89, v97
	v_fma_f32 v80, v98, v158, v80
	v_fma_f32 v81, v99, v159, v81
	v_mul_f32_e32 v76, v86, v76
	v_mul_f32_e32 v77, v87, v77
	v_mul_f32_e32 v80, v80, v88
	v_mul_f32_e32 v81, v81, v89
	v_cvt_pk_bf16_f32 v248, v76, v77
	s_nop 0
	v_cvt_pk_bf16_f32 v249, v80, v81
.LBB0_945:
	s_or_b64 exec, exec, s[0:1]
	s_movk_i32 s0, 0x1ff9
	v_cmp_lt_i32_e32 vcc, -6, v225
	v_cmp_gt_i32_e64 s[0:1], s0, v200
	s_and_b64 s[0:1], vcc, s[0:1]
	s_and_saveexec_b64 s[30:31], s[0:1]
	s_cbranch_execz .LBB0_947
	v_mov_b32_e32 v231, v230
	v_mul_f32_e32 v76, v78, v230
	v_mul_f32_e32 v77, v79, v231
	v_fma_f32 v78, v136, v176, v180
	v_fma_f32 v79, v137, v177, v181
	v_fma_f32 v76, v76, v178, v182
	v_fma_f32 v77, v77, v179, v183
	v_fma_f32 v80, v128, v164, v168
	v_fma_f32 v81, v129, v165, v169
	v_fma_f32 v68, v68, v174, v76
	v_fma_f32 v69, v69, v175, v77
	v_fma_f32 v76, v132, v172, v78
	v_fma_f32 v77, v133, v173, v79
	v_mul_f32_e32 v78, v82, v230
	v_mul_f32_e32 v79, v83, v231
	v_fma_f32 v80, v140, v160, v80
	v_fma_f32 v81, v141, v161, v81
	v_fma_f32 v78, v78, v166, v170
	v_fma_f32 v79, v79, v167, v171
	v_fma_f32 v80, v92, v152, v80
	v_fma_f32 v81, v93, v153, v81
	v_fma_f32 v78, v142, v162, v78
	v_fma_f32 v79, v143, v163, v79
	v_mul_f32_e32 v82, 0xbfb8aa3b, v80
	v_fma_f32 v78, v94, v154, v78
	v_fma_f32 v79, v95, v155, v79
	v_mul_f32_e32 v83, 0xbfb8aa3b, v81
	v_mul_f32_e32 v86, 0xbfb8aa3b, v78
	v_mul_f32_e32 v87, 0xbfb8aa3b, v79
	v_exp_f32_e32 v82, v82
	v_exp_f32_e32 v83, v83
	v_exp_f32_e32 v86, v86
	v_exp_f32_e32 v87, v87
	v_add_f32_e32 v82, 1.0, v82
	v_add_f32_e32 v83, 1.0, v83
	v_add_f32_e32 v86, 1.0, v86
	v_add_f32_e32 v87, 1.0, v87
	v_rcp_f32_e32 v82, v82
	v_rcp_f32_e32 v86, v86
	v_rcp_f32_e32 v87, v87
	v_rcp_f32_e32 v83, v83
	v_fma_f32 v68, v72, v158, v68
	v_fma_f32 v69, v73, v159, v69
	v_fma_f32 v72, v84, v156, v76
	v_fma_f32 v73, v85, v157, v77
	v_mul_f32_e32 v76, v78, v86
	v_mul_f32_e32 v77, v79, v87
	v_mul_f32_e32 v78, v80, v82
	v_mul_f32_e32 v79, v81, v83
	v_mul_f32_e32 v68, v68, v76
	v_mul_f32_e32 v69, v69, v77
	v_mul_f32_e32 v72, v72, v78
	v_mul_f32_e32 v73, v73, v79
	s_nop 0
	v_cvt_pk_bf16_f32 v120, v72, v73
	v_cvt_pk_bf16_f32 v121, v68, v69
.LBB0_947:
	s_or_b64 exec, exec, s[30:31]
	v_add_co_u32_e32 v68, vcc, 0xb000, v54
	ds_read_b128 v[76:79], v237 offset:16
	s_nop 0
	v_addc_co_u32_e32 v69, vcc, 0, v55, vcc
	v_add_co_u32_e32 v72, vcc, 0x16000, v54
	v_mov_b32_e32 v233, v232
	s_nop 0
	v_addc_co_u32_e32 v73, vcc, 0, v55, vcc
	ds_read_b128 v[84:87], v237 offset:528
	ds_read_b128 v[88:91], v237 offset:1040
	ds_read_b128 v[92:95], v237 offset:1552
	v_add_co_u32_e32 v68, vcc, 0x5000, v54
	v_mov_b32_e32 v231, v230
	s_nop 0
	v_addc_co_u32_e32 v69, vcc, 0, v55, vcc
	v_add_co_u32_e32 v54, vcc, 0x1b000, v54
	ds_read_b128 v[80:83], v237 offset:2064
	ds_read_b128 v[96:99], v237 offset:2576
	v_addc_co_u32_e32 v55, vcc, 0, v55, vcc
	v_add_co_u32_e32 v44, vcc, 0x5000, v44
	ds_read_b128 v[100:103], v237 offset:3088
	s_nop 0
	v_addc_co_u32_e32 v45, vcc, 0, v45, vcc
	ds_read_b128 v[104:107], v237 offset:3600
	v_mul_f32_e32 v64, v74, v232
	v_mul_f32_e32 v65, v75, v233
	v_mul_f32_e32 v108, v70, v230
	v_mul_f32_e32 v109, v71, v231
	v_mul_f32_e32 v110, v56, v232
	v_mul_f32_e32 v111, v57, v233
	v_mul_f32_e32 v112, v46, v230
	v_mul_f32_e32 v113, v47, v231
	v_mov_b32_dpp v68, v48 row_shr:1 row_mask:0xf bank_mask:0xf bound_ctrl:1
	v_mov_b32_dpp v44, v52 row_shr:1 row_mask:0xf bank_mask:0xf bound_ctrl:1
	v_mov_b32_dpp v72, v62 row_shr:1 row_mask:0xf bank_mask:0xf bound_ctrl:1
	v_mov_b32_dpp v54, v66 row_shr:1 row_mask:0xf bank_mask:0xf bound_ctrl:1
	v_mov_b32_dpp v69, v49 row_shr:1 row_mask:0xf bank_mask:0xf bound_ctrl:1
	v_mov_b32_dpp v45, v53 row_shr:1 row_mask:0xf bank_mask:0xf bound_ctrl:1
	v_mov_b32_dpp v73, v63 row_shr:1 row_mask:0xf bank_mask:0xf bound_ctrl:1
	v_mov_b32_dpp v55, v67 row_shr:1 row_mask:0xf bank_mask:0xf bound_ctrl:1
	v_mov_b32_dpp v70, v64 row_shr:1 row_mask:0xf bank_mask:0xf bound_ctrl:1
	v_mov_b32_dpp v46, v108 row_shr:1 row_mask:0xf bank_mask:0xf bound_ctrl:1
	v_mov_b32_dpp v74, v110 row_shr:1 row_mask:0xf bank_mask:0xf bound_ctrl:1
	v_mov_b32_dpp v56, v112 row_shr:1 row_mask:0xf bank_mask:0xf bound_ctrl:1
	v_mov_b32_dpp v71, v65 row_shr:1 row_mask:0xf bank_mask:0xf bound_ctrl:1
	v_mov_b32_dpp v47, v109 row_shr:1 row_mask:0xf bank_mask:0xf bound_ctrl:1
	v_mov_b32_dpp v75, v111 row_shr:1 row_mask:0xf bank_mask:0xf bound_ctrl:1
	v_mov_b32_dpp v57, v113 row_shr:1 row_mask:0xf bank_mask:0xf bound_ctrl:1
	s_and_saveexec_b64 s[30:31], s[4:5]
	s_cbranch_execz .LBB0_949
	v_readlane_b32 s4, v255, 38
	s_nop 1
	v_lshl_add_u32 v54, v226, 2, s4
	ds_read_b128 v[68:71], v54 offset:16
	ds_read_b128 v[72:75], v54 offset:528
	ds_read_b128 v[44:47], v54 offset:1040
	ds_read_b128 v[54:57], v54 offset:1552
; __device__ __forceinline__ unsigned cvt_pk_bf16(float lo, float hi) { unsigned r; asm("v_cvt_pk_bf16_f32 %0, %1, %2" : "=v"(r) : "v"(lo), "v"(hi)); return r; }
;     __device__ __forceinline__ void operator()(const f32x4 (&acc)[2][2][4][2], const CU2& u, int wr, int wc, int fr_, int fq_) const {
;     ...
;             for (int j = 0; j < 8; ++j) {
;                 const f32x4 xg = acc[j >> 2][0][j & 3][n] * rsv[j], xv = acc[j >> 2][1][j & 3][n] * rsv[j];
;                 const f32x4 gc = gb + g2 * xg + g1 * pg1 + g0 * pg2, vc = vb + v2 * xv + v1 * pv1 + v0 * pv2;
;                 f32x4 sg;
; #pragma unroll
;                 for (int e = 0; e < 4; ++e) sg[e] = __builtin_amdgcn_rcpf(1.f + __expf(-gc[e]));
;                 const f32x4 o4 = gc * sg * vc;
;                 pg2 = pg1; pg1 = xg; pv2 = pv1; pv1 = xv;
;                 if (rb + j >= 2 && tb + j < T_) { u32x2 w; w.x = cvt_pk_bf16(o4[0], o4[1]); w.y = cvt_pk_bf16(o4[2], o4[3]); *(u32x2*)(act + (size_t)(tb + j) * FF_ + 128 * u.pn + cl + 4 * n) = w; }
.LBB0_949:
	s_or_b64 exec, exec, s[30:31]
	v_mov_b32_e32 v229, v228
	v_mov_b32_e32 v114, v228
	v_mov_b32_e32 v115, v228
	v_mul_f32_e32 v60, v60, v114
	v_mul_f32_e32 v61, v61, v115
	v_mul_f32_e32 v58, v58, v228
	v_mul_f32_e32 v59, v59, v229
	v_mul_f32_e32 v42, v42, v114
	v_mul_f32_e32 v43, v43, v115
	v_mul_f32_e32 v40, v40, v228
	v_mul_f32_e32 v41, v41, v229
	s_and_saveexec_b64 s[4:5], s[10:11]
	s_cbranch_execz .LBB0_951
	s_waitcnt lgkmcnt(0)
	v_fma_f32 v114, v42, v102, v106
	v_fma_f32 v115, v43, v103, v107
	v_fma_f32 v116, v40, v100, v104
	v_fma_f32 v117, v41, v101, v105
	s_waitcnt lgkmcnt(0)
	v_fma_f32 v114, v98, v56, v114
	v_fma_f32 v115, v99, v57, v115
	v_fma_f32 v116, v96, v54, v116
	v_fma_f32 v117, v97, v55, v117
	v_fma_f32 v74, v82, v74, v114
	v_fma_f32 v75, v83, v75, v115
	v_fma_f32 v72, v80, v72, v116
	v_fma_f32 v73, v81, v73, v117
	v_fma_f32 v114, v60, v90, v94
	v_fma_f32 v115, v61, v91, v95
	v_fma_f32 v116, v58, v88, v92
	v_fma_f32 v117, v59, v89, v93
	v_fma_f32 v114, v86, v46, v114
	v_fma_f32 v115, v87, v47, v115
	v_fma_f32 v116, v84, v44, v116
	v_fma_f32 v117, v85, v45, v117
	v_fma_f32 v70, v78, v70, v114
	v_fma_f32 v71, v79, v71, v115
	v_fma_f32 v68, v76, v68, v116
	v_fma_f32 v69, v77, v69, v117
	v_mul_f32_e32 v116, 0xbfb8aa3b, v70
	v_mul_f32_e32 v114, 0xbfb8aa3b, v68
	v_mul_f32_e32 v115, 0xbfb8aa3b, v69
	v_mul_f32_e32 v117, 0xbfb8aa3b, v71
	v_exp_f32_e32 v114, v114
	v_exp_f32_e32 v115, v115
	v_exp_f32_e32 v116, v116
	v_exp_f32_e32 v117, v117
	v_add_f32_e32 v114, 1.0, v114
	v_add_f32_e32 v115, 1.0, v115
	v_add_f32_e32 v116, 1.0, v116
	v_add_f32_e32 v117, 1.0, v117
	v_rcp_f32_e32 v114, v114
	v_rcp_f32_e32 v115, v115
	v_rcp_f32_e32 v116, v116
	v_rcp_f32_e32 v117, v117
	v_mul_f32_e32 v68, v68, v114
	v_mul_f32_e32 v69, v69, v115
	s_nop 0
	v_mul_f32_e32 v68, v72, v68
	v_mul_f32_e32 v69, v73, v69
	v_mul_f32_e32 v70, v70, v116
	v_mul_f32_e32 v71, v71, v117
	v_cvt_pk_bf16_f32 v150, v68, v69
	s_nop 0
	v_mul_f32_e32 v70, v74, v70
	v_mul_f32_e32 v71, v75, v71
	s_nop 0
	v_cvt_pk_bf16_f32 v151, v70, v71
	v_mad_i64_i32 v[70:71], s[10:11], v200, s37, v[50:51]
	global_store_dwordx4 v[70:71], v[148:151], off
.LBB0_951:
	s_or_b64 exec, exec, s[4:5]
	v_mov_b32_e32 v225, v224
	s_waitcnt lgkmcnt(0)
	v_mov_b32_e32 v68, v224
	v_mov_b32_e32 v69, v224
	v_mul_f32_e32 v38, v38, v68
	v_mul_f32_e32 v39, v39, v69
	v_mul_f32_e32 v36, v36, v224
	v_mul_f32_e32 v37, v37, v225
	v_mul_f32_e32 v34, v34, v68
	v_mul_f32_e32 v35, v35, v69
	v_mul_f32_e32 v32, v32, v224
	v_mul_f32_e32 v33, v33, v225
	s_and_saveexec_b64 s[4:5], s[6:7]
	s_cbranch_execz .LBB0_953
	v_fma_f32 v68, v34, v102, v106
	v_fma_f32 v69, v35, v103, v107
	v_fma_f32 v70, v32, v100, v104
	v_fma_f32 v71, v33, v101, v105
	v_fma_f32 v68, v42, v98, v68
	v_fma_f32 v69, v43, v99, v69
	v_fma_f32 v70, v40, v96, v70
	v_fma_f32 v71, v41, v97, v71
	v_fma_f32 v56, v82, v56, v68
	v_fma_f32 v57, v83, v57, v69
	v_fma_f32 v54, v80, v54, v70
	v_fma_f32 v55, v81, v55, v71
	v_fma_f32 v68, v38, v90, v94
	v_fma_f32 v69, v39, v91, v95
	v_fma_f32 v70, v36, v88, v92
	v_fma_f32 v71, v37, v89, v93
	v_fma_f32 v68, v60, v86, v68
	v_fma_f32 v69, v61, v87, v69
	v_fma_f32 v70, v58, v84, v70
	v_fma_f32 v71, v59, v85, v71
	v_fma_f32 v46, v78, v46, v68
	v_fma_f32 v47, v79, v47, v69
	v_fma_f32 v44, v76, v44, v70
	v_fma_f32 v45, v77, v45, v71
	v_mul_f32_e32 v70, 0xbfb8aa3b, v46
	v_mul_f32_e32 v68, 0xbfb8aa3b, v44
	v_mul_f32_e32 v69, 0xbfb8aa3b, v45
	v_mul_f32_e32 v71, 0xbfb8aa3b, v47
	v_exp_f32_e32 v68, v68
	v_exp_f32_e32 v69, v69
	v_exp_f32_e32 v70, v70
	v_exp_f32_e32 v71, v71
	v_add_f32_e32 v68, 1.0, v68
	v_add_f32_e32 v69, 1.0, v69
	v_add_f32_e32 v70, 1.0, v70
	v_add_f32_e32 v71, 1.0, v71
	v_rcp_f32_e32 v68, v68
	v_rcp_f32_e32 v69, v69
	v_rcp_f32_e32 v70, v70
	v_rcp_f32_e32 v71, v71
	v_mul_f32_e32 v44, v44, v68
	v_mul_f32_e32 v45, v45, v69
	s_nop 0
	v_mul_f32_e32 v44, v54, v44
	v_mul_f32_e32 v45, v55, v45
	v_mul_f32_e32 v46, v46, v70
	v_mul_f32_e32 v47, v47, v71
	v_cvt_pk_bf16_f32 v146, v44, v45
	s_nop 0
	v_mul_f32_e32 v46, v56, v46
	v_mul_f32_e32 v47, v57, v47
	s_nop 0
	v_cvt_pk_bf16_f32 v147, v46, v47
	v_mad_i64_i32 v[46:47], s[6:7], v223, s37, v[50:51]
	global_store_dwordx4 v[46:47], v[144:147], off
.LBB0_953:
	s_or_b64 exec, exec, s[4:5]
	v_mov_b32_e32 v223, v222
	v_mov_b32_e32 v44, v222
	v_mov_b32_e32 v45, v222
	v_mul_f32_e32 v30, v30, v44
	v_mul_f32_e32 v31, v31, v45
	v_mul_f32_e32 v28, v28, v222
	v_mul_f32_e32 v29, v29, v223
	v_mul_f32_e32 v26, v26, v44
	v_mul_f32_e32 v27, v27, v45
	v_mul_f32_e32 v24, v24, v222
	v_mul_f32_e32 v25, v25, v223
	s_and_saveexec_b64 s[4:5], s[8:9]
	s_cbranch_execz .LBB0_955
	v_fma_f32 v44, v26, v102, v106
	v_fma_f32 v45, v27, v103, v107
	v_fma_f32 v46, v24, v100, v104
	v_fma_f32 v47, v25, v101, v105
	v_fma_f32 v44, v34, v98, v44
	v_fma_f32 v45, v35, v99, v45
	v_fma_f32 v46, v32, v96, v46
	v_fma_f32 v47, v33, v97, v47
	v_fma_f32 v42, v42, v82, v44
	v_fma_f32 v43, v43, v83, v45
	v_fma_f32 v40, v40, v80, v46
	v_fma_f32 v41, v41, v81, v47
	v_fma_f32 v44, v30, v90, v94
	v_fma_f32 v45, v31, v91, v95
	v_fma_f32 v46, v28, v88, v92
	v_fma_f32 v47, v29, v89, v93
	v_fma_f32 v44, v38, v86, v44
	v_fma_f32 v45, v39, v87, v45
	v_fma_f32 v46, v36, v84, v46
	v_fma_f32 v47, v37, v85, v47
	v_fma_f32 v44, v60, v78, v44
	v_fma_f32 v45, v61, v79, v45
	v_fma_f32 v46, v58, v76, v46
	v_fma_f32 v47, v59, v77, v47
	v_mul_f32_e32 v56, 0xbfb8aa3b, v44
	v_mul_f32_e32 v54, 0xbfb8aa3b, v46
	v_mul_f32_e32 v55, 0xbfb8aa3b, v47
	v_mul_f32_e32 v57, 0xbfb8aa3b, v45
	v_exp_f32_e32 v54, v54
	v_exp_f32_e32 v55, v55
	v_exp_f32_e32 v56, v56
	v_exp_f32_e32 v57, v57
	v_add_f32_e32 v54, 1.0, v54
	v_add_f32_e32 v55, 1.0, v55
	v_add_f32_e32 v56, 1.0, v56
	v_add_f32_e32 v57, 1.0, v57
	v_rcp_f32_e32 v54, v54
	v_rcp_f32_e32 v55, v55
	v_rcp_f32_e32 v56, v56
	v_rcp_f32_e32 v57, v57
	v_mul_f32_e32 v46, v46, v54
	v_mul_f32_e32 v47, v47, v55
	s_nop 0
	v_mul_f32_e32 v40, v40, v46
	v_mul_f32_e32 v41, v41, v47
	v_mul_f32_e32 v44, v44, v56
	v_mul_f32_e32 v45, v45, v57
	v_cvt_pk_bf16_f32 v186, v40, v41
	s_nop 0
	v_mul_f32_e32 v42, v42, v44
	v_mul_f32_e32 v43, v43, v45
	s_nop 0
	v_cvt_pk_bf16_f32 v187, v42, v43
	v_mad_i64_i32 v[42:43], s[6:7], v221, s37, v[50:51]
	global_store_dwordx4 v[42:43], v[184:187], off
; __device__ __forceinline__ unsigned cvt_pk_bf16(float lo, float hi) { unsigned r; asm("v_cvt_pk_bf16_f32 %0, %1, %2" : "=v"(r) : "v"(lo), "v"(hi)); return r; }
;     __device__ __forceinline__ void operator()(const f32x4 (&acc)[2][2][4][2], const CU2& u, int wr, int wc, int fr_, int fq_) const {
;     ...
;             for (int j = 0; j < 8; ++j) {
;                 const f32x4 xg = acc[j >> 2][0][j & 3][n] * rsv[j], xv = acc[j >> 2][1][j & 3][n] * rsv[j];
;                 const f32x4 gc = gb + g2 * xg + g1 * pg1 + g0 * pg2, vc = vb + v2 * xv + v1 * pv1 + v0 * pv2;
;                 f32x4 sg;
; #pragma unroll
;                 for (int e = 0; e < 4; ++e) sg[e] = __builtin_amdgcn_rcpf(1.f + __expf(-gc[e]));
;                 const f32x4 o4 = gc * sg * vc;
;                 pg2 = pg1; pg1 = xg; pv2 = pv1; pv1 = xv;
;                 if (rb + j >= 2 && tb + j < T_) { u32x2 w; w.x = cvt_pk_bf16(o4[0], o4[1]); w.y = cvt_pk_bf16(o4[2], o4[3]); *(u32x2*)(act + (size_t)(tb + j) * FF_ + 128 * u.pn + cl + 4 * n) = w; }
.LBB0_955:
	s_or_b64 exec, exec, s[4:5]
	v_mov_b32_e32 v221, v220
	v_mov_b32_e32 v40, v220
	v_mov_b32_e32 v41, v220
	v_mul_f32_e32 v22, v22, v40
	v_mul_f32_e32 v23, v23, v41
	v_mul_f32_e32 v20, v20, v220
	v_mul_f32_e32 v21, v21, v221
	v_mul_f32_e32 v18, v18, v40
	v_mul_f32_e32 v19, v19, v41
	v_mul_f32_e32 v16, v16, v220
	v_mul_f32_e32 v17, v17, v221
	s_and_saveexec_b64 s[4:5], s[12:13]
	s_cbranch_execz .LBB0_957
	v_fma_f32 v40, v18, v102, v106
	v_fma_f32 v41, v19, v103, v107
	v_fma_f32 v42, v16, v100, v104
	v_fma_f32 v43, v17, v101, v105
	v_fma_f32 v40, v26, v98, v40
	v_fma_f32 v41, v27, v99, v41
	v_fma_f32 v42, v24, v96, v42
	v_fma_f32 v43, v25, v97, v43
	v_fma_f32 v34, v34, v82, v40
	v_fma_f32 v35, v35, v83, v41
	v_fma_f32 v32, v32, v80, v42
	v_fma_f32 v33, v33, v81, v43
	v_fma_f32 v40, v22, v90, v94
	v_fma_f32 v41, v23, v91, v95
	v_fma_f32 v42, v20, v88, v92
	v_fma_f32 v43, v21, v89, v93
	v_fma_f32 v40, v30, v86, v40
	v_fma_f32 v41, v31, v87, v41
	v_fma_f32 v42, v28, v84, v42
	v_fma_f32 v43, v29, v85, v43
	v_fma_f32 v38, v38, v78, v40
	v_fma_f32 v39, v39, v79, v41
	v_fma_f32 v36, v36, v76, v42
	v_fma_f32 v37, v37, v77, v43
	v_mul_f32_e32 v42, 0xbfb8aa3b, v38
	v_mul_f32_e32 v40, 0xbfb8aa3b, v36
	v_mul_f32_e32 v41, 0xbfb8aa3b, v37
	v_mul_f32_e32 v43, 0xbfb8aa3b, v39
	v_exp_f32_e32 v40, v40
	v_exp_f32_e32 v41, v41
	v_exp_f32_e32 v42, v42
	v_exp_f32_e32 v43, v43
	v_add_f32_e32 v40, 1.0, v40
	v_add_f32_e32 v41, 1.0, v41
	v_add_f32_e32 v42, 1.0, v42
	v_add_f32_e32 v43, 1.0, v43
	v_rcp_f32_e32 v40, v40
	v_rcp_f32_e32 v41, v41
	v_rcp_f32_e32 v42, v42
	v_rcp_f32_e32 v43, v43
	v_mul_f32_e32 v36, v36, v40
	v_mul_f32_e32 v37, v37, v41
	s_nop 0
	v_mul_f32_e32 v32, v32, v36
	v_mul_f32_e32 v33, v33, v37
	v_mul_f32_e32 v38, v38, v42
	v_mul_f32_e32 v39, v39, v43
	v_cvt_pk_bf16_f32 v190, v32, v33
	s_nop 0
	v_mul_f32_e32 v34, v34, v38
	v_mul_f32_e32 v35, v35, v39
	s_nop 0
	v_cvt_pk_bf16_f32 v191, v34, v35
	v_mad_i64_i32 v[34:35], s[6:7], v219, s37, v[50:51]
	global_store_dwordx4 v[34:35], v[188:191], off
.LBB0_957:
	s_or_b64 exec, exec, s[4:5]
	v_mov_b32_e32 v219, v218
	v_mov_b32_e32 v32, v218
	v_mov_b32_e32 v33, v218
	v_mul_f32_e32 v14, v14, v32
	v_mul_f32_e32 v15, v15, v33
	v_mul_f32_e32 v12, v12, v218
	v_mul_f32_e32 v13, v13, v219
	v_mul_f32_e32 v10, v10, v32
	v_mul_f32_e32 v11, v11, v33
	v_mul_f32_e32 v8, v8, v218
	v_mul_f32_e32 v9, v9, v219
	s_and_saveexec_b64 s[4:5], s[14:15]
	s_cbranch_execz .LBB0_959
	v_fma_f32 v32, v10, v102, v106
	v_fma_f32 v33, v11, v103, v107
	v_fma_f32 v34, v8, v100, v104
	v_fma_f32 v35, v9, v101, v105
	v_fma_f32 v32, v18, v98, v32
	v_fma_f32 v33, v19, v99, v33
	v_fma_f32 v34, v16, v96, v34
	v_fma_f32 v35, v17, v97, v35
	v_fma_f32 v26, v26, v82, v32
	v_fma_f32 v27, v27, v83, v33
	v_fma_f32 v24, v24, v80, v34
	v_fma_f32 v25, v25, v81, v35
	v_fma_f32 v32, v14, v90, v94
	v_fma_f32 v33, v15, v91, v95
	v_fma_f32 v34, v12, v88, v92
	v_fma_f32 v35, v13, v89, v93
	v_fma_f32 v32, v22, v86, v32
	v_fma_f32 v33, v23, v87, v33
	v_fma_f32 v34, v20, v84, v34
	v_fma_f32 v35, v21, v85, v35
	v_fma_f32 v30, v30, v78, v32
	v_fma_f32 v31, v31, v79, v33
	v_fma_f32 v28, v28, v76, v34
	v_fma_f32 v29, v29, v77, v35
	v_mul_f32_e32 v34, 0xbfb8aa3b, v30
	v_mul_f32_e32 v32, 0xbfb8aa3b, v28
	v_mul_f32_e32 v33, 0xbfb8aa3b, v29
	v_mul_f32_e32 v35, 0xbfb8aa3b, v31
	v_exp_f32_e32 v32, v32
	v_exp_f32_e32 v33, v33
	v_exp_f32_e32 v34, v34
	v_exp_f32_e32 v35, v35
	v_add_f32_e32 v32, 1.0, v32
	v_add_f32_e32 v33, 1.0, v33
	v_add_f32_e32 v34, 1.0, v34
	v_add_f32_e32 v35, 1.0, v35
	v_rcp_f32_e32 v32, v32
	v_rcp_f32_e32 v33, v33
	v_rcp_f32_e32 v34, v34
	v_rcp_f32_e32 v35, v35
	v_mul_f32_e32 v28, v28, v32
	v_mul_f32_e32 v29, v29, v33
	s_nop 0
	v_mul_f32_e32 v24, v24, v28
	v_mul_f32_e32 v25, v25, v29
	v_mul_f32_e32 v30, v30, v34
	v_mul_f32_e32 v31, v31, v35
	v_cvt_pk_bf16_f32 v194, v24, v25
	s_nop 0
	v_mul_f32_e32 v26, v26, v30
	v_mul_f32_e32 v27, v27, v31
	s_nop 0
	v_cvt_pk_bf16_f32 v195, v26, v27
	v_mad_i64_i32 v[26:27], s[6:7], v217, s37, v[50:51]
	global_store_dwordx4 v[26:27], v[192:195], off
; #define LAS __attribute__((address_space(3)))
; __device__ __forceinline__ unsigned cvt_pk_bf16(float lo, float hi) { unsigned r; asm("v_cvt_pk_bf16_f32 %0, %1, %2" : "=v"(r) : "v"(lo), "v"(hi)); return r; }
;     __device__ __forceinline__ void operator()(const f32x4 (&acc)[2][2][4][2], const CU2& u, int wr, int wc, int fr_, int fq_) const {
;     ...
;             f32x4 pg2 = acc[1][0][2][n] * rsv[6], pg1 = acc[1][0][3][n] * rsv[7], pv2 = acc[1][1][2][n] * rsv[6], pv1 = acc[1][1][3][n] * rsv[7];
; #pragma unroll
;             for (int e = 0; e < 4; ++e) {
;                 pg2[e] = __int_as_float(__builtin_amdgcn_mov_dpp(__float_as_int(pg2[e]), 0x111, 0xF, 0xF, true)); pg1[e] = __int_as_float(__builtin_amdgcn_mov_dpp(__float_as_int(pg1[e]), 0x111, 0xF, 0xF, true));
;                 pv2[e] = __int_as_float(__builtin_amdgcn_mov_dpp(__float_as_int(pv2[e]), 0x111, 0xF, 0xF, true)); pv1[e] = __int_as_float(__builtin_amdgcn_mov_dpp(__float_as_int(pv1[e]), 0x111, 0xF, 0xF, true));
;             }
;             if (fr == 0 && wr == 1) { pg2 = *(const LAS f32x4*)(hal + cl + 4 * n); pg1 = *(const LAS f32x4*)(hal + 256 + cl + 4 * n); pv2 = *(const LAS f32x4*)(hal + 128 + cl + 4 * n); pv1 = *(const LAS f32x4*)(hal + 384 + cl + 4 * n); }
; #pragma unroll
;             for (int j = 0; j < 8; ++j) {
;                 const f32x4 xg = acc[j >> 2][0][j & 3][n] * rsv[j], xv = acc[j >> 2][1][j & 3][n] * rsv[j];
;                 const f32x4 gc = gb + g2 * xg + g1 * pg1 + g0 * pg2, vc = vb + v2 * xv + v1 * pv1 + v0 * pv2;
;                 f32x4 sg;
; #pragma unroll
;                 for (int e = 0; e < 4; ++e) sg[e] = __builtin_amdgcn_rcpf(1.f + __expf(-gc[e]));
;                 const f32x4 o4 = gc * sg * vc;
;                 pg2 = pg1; pg1 = xg; pv2 = pv1; pv1 = xv;
;                 if (rb + j >= 2 && tb + j < T_) { u32x2 w; w.x = cvt_pk_bf16(o4[0], o4[1]); w.y = cvt_pk_bf16(o4[2], o4[3]); *(u32x2*)(act + (size_t)(tb + j) * FF_ + 128 * u.pn + cl + 4 * n) = w; }
.LBB0_959:
	s_or_b64 exec, exec, s[4:5]
	v_mov_b32_e32 v217, v216
	v_mov_b32_e32 v24, v216
	v_mov_b32_e32 v25, v216
	v_mul_f32_e32 v6, v6, v24
	v_mul_f32_e32 v7, v7, v25
	v_mul_f32_e32 v4, v4, v216
	v_mul_f32_e32 v5, v5, v217
	v_mul_f32_e32 v2, v2, v24
	v_mul_f32_e32 v3, v3, v25
	v_mul_f32_e32 v0, v0, v216
	v_mul_f32_e32 v1, v1, v217
	s_and_saveexec_b64 s[4:5], s[26:27]
	s_cbranch_execz .LBB0_961
	v_fma_f32 v24, v2, v102, v106
	v_fma_f32 v25, v3, v103, v107
	v_fma_f32 v26, v0, v100, v104
	v_fma_f32 v27, v1, v101, v105
	v_fma_f32 v24, v10, v98, v24
	v_fma_f32 v25, v11, v99, v25
	v_fma_f32 v26, v8, v96, v26
	v_fma_f32 v27, v9, v97, v27
	v_fma_f32 v18, v18, v82, v24
	v_fma_f32 v19, v19, v83, v25
	v_fma_f32 v16, v16, v80, v26
	v_fma_f32 v17, v17, v81, v27
	v_fma_f32 v24, v6, v90, v94
	v_fma_f32 v25, v7, v91, v95
	v_fma_f32 v26, v4, v88, v92
	v_fma_f32 v27, v5, v89, v93
	v_fma_f32 v24, v14, v86, v24
	v_fma_f32 v25, v15, v87, v25
	v_fma_f32 v26, v12, v84, v26
	v_fma_f32 v27, v13, v85, v27
	v_fma_f32 v22, v22, v78, v24
	v_fma_f32 v23, v23, v79, v25
	v_fma_f32 v20, v20, v76, v26
	v_fma_f32 v21, v21, v77, v27
	v_mul_f32_e32 v26, 0xbfb8aa3b, v22
	v_mul_f32_e32 v24, 0xbfb8aa3b, v20
	v_mul_f32_e32 v25, 0xbfb8aa3b, v21
	v_mul_f32_e32 v27, 0xbfb8aa3b, v23
	v_exp_f32_e32 v24, v24
	v_exp_f32_e32 v25, v25
	v_exp_f32_e32 v26, v26
	v_exp_f32_e32 v27, v27
	v_add_f32_e32 v24, 1.0, v24
	v_add_f32_e32 v25, 1.0, v25
	v_add_f32_e32 v26, 1.0, v26
	v_add_f32_e32 v27, 1.0, v27
	v_rcp_f32_e32 v24, v24
	v_rcp_f32_e32 v25, v25
	v_rcp_f32_e32 v26, v26
	v_rcp_f32_e32 v27, v27
	v_mul_f32_e32 v20, v20, v24
	v_mul_f32_e32 v21, v21, v25
	s_nop 0
	v_mul_f32_e32 v16, v16, v20
	v_mul_f32_e32 v17, v17, v21
	v_mul_f32_e32 v22, v22, v26
	v_mul_f32_e32 v23, v23, v27
	v_cvt_pk_bf16_f32 v198, v16, v17
	s_nop 0
	v_mul_f32_e32 v18, v18, v22
	v_mul_f32_e32 v19, v19, v23
	s_nop 0
	v_cvt_pk_bf16_f32 v199, v18, v19
	v_mad_i64_i32 v[18:19], s[6:7], v246, s37, v[50:51]
	global_store_dwordx4 v[18:19], v[196:199], off
.LBB0_961:
	s_or_b64 exec, exec, s[4:5]
	s_and_saveexec_b64 s[4:5], s[28:29]
	s_cbranch_execz .LBB0_963
	v_fma_f32 v16, v110, v102, v106
	v_fma_f32 v17, v111, v103, v107
	v_fma_f32 v18, v62, v100, v104
	v_fma_f32 v19, v63, v101, v105
	v_fma_f32 v16, v2, v98, v16
	v_fma_f32 v17, v3, v99, v17
	v_fma_f32 v18, v0, v96, v18
	v_fma_f32 v19, v1, v97, v19
	v_fma_f32 v10, v10, v82, v16
	v_fma_f32 v11, v11, v83, v17
	v_fma_f32 v8, v8, v80, v18
	v_fma_f32 v9, v9, v81, v19
	v_fma_f32 v16, v64, v90, v94
	v_fma_f32 v17, v65, v91, v95
	v_fma_f32 v18, v48, v88, v92
	v_fma_f32 v19, v49, v89, v93
	v_fma_f32 v16, v6, v86, v16
	v_fma_f32 v17, v7, v87, v17
	v_fma_f32 v18, v4, v84, v18
	v_fma_f32 v19, v5, v85, v19
	v_fma_f32 v14, v14, v78, v16
	v_fma_f32 v15, v15, v79, v17
	v_fma_f32 v12, v12, v76, v18
	v_fma_f32 v13, v13, v77, v19
	v_mul_f32_e32 v18, 0xbfb8aa3b, v14
	v_mul_f32_e32 v16, 0xbfb8aa3b, v12
	v_mul_f32_e32 v17, 0xbfb8aa3b, v13
	v_mul_f32_e32 v19, 0xbfb8aa3b, v15
	v_exp_f32_e32 v16, v16
	v_exp_f32_e32 v17, v17
	v_exp_f32_e32 v18, v18
	v_exp_f32_e32 v19, v19
	v_add_f32_e32 v16, 1.0, v16
	v_add_f32_e32 v17, 1.0, v17
	v_add_f32_e32 v18, 1.0, v18
	v_add_f32_e32 v19, 1.0, v19
	v_rcp_f32_e32 v16, v16
	v_rcp_f32_e32 v17, v17
	v_rcp_f32_e32 v18, v18
	v_rcp_f32_e32 v19, v19
	v_mul_f32_e32 v12, v12, v16
	v_mul_f32_e32 v13, v13, v17
	s_nop 0
	v_mul_f32_e32 v8, v8, v12
	v_mul_f32_e32 v9, v9, v13
	v_mul_f32_e32 v14, v14, v18
	v_mul_f32_e32 v15, v15, v19
	v_cvt_pk_bf16_f32 v250, v8, v9
	s_nop 0
	v_mul_f32_e32 v10, v10, v14
	v_mul_f32_e32 v11, v11, v15
	s_nop 0
	v_cvt_pk_bf16_f32 v251, v10, v11
	v_mad_i64_i32 v[10:11], s[6:7], v245, s37, v[50:51]
	global_store_dwordx4 v[10:11], v[248:251], off
.LBB0_963:
	s_or_b64 exec, exec, s[4:5]
	s_and_saveexec_b64 s[4:5], s[0:1]
	s_cbranch_execz .LBB0_965
	v_fma_f32 v12, v52, v88, v92
	v_fma_f32 v13, v53, v89, v93
	v_fma_f32 v8, v112, v102, v106
	v_fma_f32 v9, v113, v103, v107
	v_fma_f32 v12, v48, v84, v12
	v_fma_f32 v13, v49, v85, v13
	v_fma_f32 v10, v66, v100, v104
	v_fma_f32 v11, v67, v101, v105
	v_fma_f32 v4, v4, v76, v12
	v_fma_f32 v5, v5, v77, v13
	v_fma_f32 v8, v110, v98, v8
	v_fma_f32 v9, v111, v99, v9
	v_mul_f32_e32 v12, 0xbfb8aa3b, v4
	v_exp_f32_e32 v14, v12
	v_fma_f32 v12, v108, v90, v94
	v_fma_f32 v13, v109, v91, v95
	v_fma_f32 v10, v62, v96, v10
	v_fma_f32 v11, v63, v97, v11
	v_fma_f32 v12, v64, v86, v12
	v_fma_f32 v13, v65, v87, v13
	v_fma_f32 v2, v2, v82, v8
	v_fma_f32 v3, v3, v83, v9
	v_fma_f32 v6, v6, v78, v12
	v_fma_f32 v7, v7, v79, v13
	v_add_f32_e32 v12, 1.0, v14
	v_mul_f32_e32 v13, 0xbfb8aa3b, v5
	v_mul_f32_e32 v14, 0xbfb8aa3b, v6
	v_mul_f32_e32 v15, 0xbfb8aa3b, v7
	v_exp_f32_e32 v13, v13
	v_exp_f32_e32 v14, v14
	v_exp_f32_e32 v15, v15
	v_rcp_f32_e32 v12, v12
	v_add_f32_e32 v13, 1.0, v13
	v_add_f32_e32 v14, 1.0, v14
	v_add_f32_e32 v15, 1.0, v15
	v_rcp_f32_e32 v14, v14
	v_rcp_f32_e32 v15, v15
	v_rcp_f32_e32 v13, v13
	v_fma_f32 v0, v0, v80, v10
	v_fma_f32 v1, v1, v81, v11
	v_mul_f32_e32 v6, v6, v14
	v_mul_f32_e32 v7, v7, v15
	v_mul_f32_e32 v4, v4, v12
	v_mul_f32_e32 v5, v5, v13
	v_mul_f32_e32 v2, v2, v6
	v_mul_f32_e32 v3, v3, v7
	v_mul_f32_e32 v0, v0, v4
	v_mul_f32_e32 v1, v1, v5
	s_nop 0
	v_cvt_pk_bf16_f32 v122, v0, v1
	v_cvt_pk_bf16_f32 v123, v2, v3
	v_mad_i64_i32 v[2:3], s[0:1], v244, s37, v[50:51]
	global_store_dwordx4 v[2:3], v[120:123], off
